# conv_mat scaled loops: issue the 8 norm-weight loads together with the tile loads (one wait) instead of 4 serialized round trips
# baseline (speedup 1.0000x reference)
; #define LAS __attribute__((address_space(3)))
; __device__ __forceinline__ unsigned pkbf(float lo, float hi) { const f32x2_m v = {lo, hi}; const bf16x2_m b = __builtin_convertvector(v, bf16x2_m); return __builtin_bit_cast(unsigned, b); }
; __device__ __forceinline__ void tr_item(const float* W, const float* nw, int K, int N, bf16* WT, int k0, int n0, int drow0, LAS float* scr, int lane) {
;     ...
;     asm volatile("s_waitcnt lgkmcnt(0)" ::: "memory");
;     const int c = lane & 7;
; #pragma unroll
;     for (int j = 0; j < 4; ++j) { const int n = (lane >> 3) + 8 * j; const LAS float* s = scr + (8 * c) * 33 + n;
;         v4u o; o.x = pkbf(s[0 * 33], s[1 * 33]); o.y = pkbf(s[2 * 33], s[3 * 33]); o.z = pkbf(s[4 * 33], s[5 * 33]); o.w = pkbf(s[6 * 33], s[7 * 33]);
;         *(v4u*)(WT + (size_t)(drow0 + n) * K + k0 + 8 * c) = o; }
;     asm volatile("s_waitcnt lgkmcnt(0)" ::: "memory");
.LBB0_20:
	s_waitcnt lgkmcnt(0)
	ds_read2_b32 v[6:7], v45 offset0:33 offset1:41
	ds_read2_b32 v[8:9], v45 offset1:8
	ds_read2_b32 v[10:11], v45 offset0:66 offset1:74
	ds_read2_b32 v[12:13], v45 offset0:99 offset1:107
	ds_read2_b32 v[14:15], v45 offset0:132 offset1:140
	ds_read2_b32 v[16:17], v45 offset0:165 offset1:173
	ds_read2_b32 v[18:19], v45 offset0:198 offset1:206
	ds_read2_b32 v[20:21], v45 offset0:231 offset1:239
	v_add_u32_e32 v24, s35, v224
	s_ashr_i32 s9, s8, 31
	v_ashrrev_i32_e32 v25, 31, v24
	v_lshl_add_u64 v[22:23], s[8:9], 1, v[38:39]
	v_lshlrev_b64 v[24:25], 12, v[24:25]
	s_waitcnt lgkmcnt(6)
	v_cvt_pk_bf16_f32 v2, v8, v6
	s_waitcnt lgkmcnt(4)
	v_cvt_pk_bf16_f32 v3, v10, v12
	s_waitcnt lgkmcnt(2)
	v_cvt_pk_bf16_f32 v4, v14, v16
	s_waitcnt lgkmcnt(0)
	v_cvt_pk_bf16_f32 v5, v18, v20
	v_lshl_add_u64 v[24:25], v[22:23], 0, v[24:25]
	v_add_u32_e32 v6, s35, v1
	global_store_dwordx4 v[24:25], v[2:5], off
	s_add_i32 s33, s33, s64
	s_add_i32 s3, s3, s14
	v_cvt_pk_bf16_f32 v2, v9, v7
	v_ashrrev_i32_e32 v7, 31, v6
	v_cvt_pk_bf16_f32 v3, v11, v13
	v_cvt_pk_bf16_f32 v4, v15, v17
	v_cvt_pk_bf16_f32 v5, v19, v21
	v_lshlrev_b64 v[6:7], 12, v[6:7]
	ds_read2_b32 v[8:9], v45 offset0:49 offset1:57
	ds_read2_b32 v[10:11], v45 offset0:16 offset1:24
	ds_read2_b32 v[12:13], v45 offset0:82 offset1:90
	ds_read2_b32 v[14:15], v45 offset0:115 offset1:123
	ds_read2_b32 v[16:17], v45 offset0:148 offset1:156
	ds_read2_b32 v[18:19], v45 offset0:181 offset1:189
	ds_read2_b32 v[20:21], v45 offset0:214 offset1:222
	ds_read2_b32 v[24:25], v45 offset0:247 offset1:255
	v_lshl_add_u64 v[6:7], v[22:23], 0, v[6:7]
	global_store_dwordx4 v[6:7], v[2:5], off
	v_add_u32_e32 v6, s35, v35
	v_ashrrev_i32_e32 v7, 31, v6
	v_lshlrev_b64 v[6:7], 12, v[6:7]
	s_waitcnt lgkmcnt(6)
	v_cvt_pk_bf16_f32 v2, v10, v8
	s_waitcnt lgkmcnt(4)
	v_cvt_pk_bf16_f32 v3, v12, v14
	s_waitcnt lgkmcnt(2)
	v_cvt_pk_bf16_f32 v4, v16, v18
	s_waitcnt lgkmcnt(0)
	v_cvt_pk_bf16_f32 v5, v20, v24
	v_lshl_add_u64 v[6:7], v[22:23], 0, v[6:7]
	global_store_dwordx4 v[6:7], v[2:5], off
	v_add_u32_e32 v6, s35, v43
	v_ashrrev_i32_e32 v7, 31, v6
	v_lshlrev_b64 v[6:7], 12, v[6:7]
	v_cvt_pk_bf16_f32 v2, v11, v9
	v_cvt_pk_bf16_f32 v3, v13, v15
	v_cvt_pk_bf16_f32 v4, v17, v19
	v_cvt_pk_bf16_f32 v5, v21, v25
	v_lshl_add_u64 v[6:7], v[22:23], 0, v[6:7]
	global_store_dwordx4 v[6:7], v[2:5], off
	s_waitcnt lgkmcnt(0)
	s_add_i32 s15, s15, s20
	s_cmpk_lt_i32 s33, 0x2c00
	s_cbranch_scc0 .LBB0_33

; #define LAS __attribute__((address_space(3)))
; __device__ __forceinline__ void tr_item(const float* W, const float* nw, int K, int N, bf16* WT, int k0, int n0, int drow0, LAS float* scr, int lane) {
;     { const int r = lane >> 3, c4 = lane & 7; f32x4 v[8];
; #pragma unroll
;       for (int i = 0; i < 8; ++i) v[i] = *(const f32x4*)(W + (size_t)(k0 + 8 * i + r) * N + n0 + 4 * c4);
; #pragma unroll
;       for (int i = 0; i < 8; ++i) { LAS float* d = scr + (8 * i + r) * 33 + 4 * c4; const float s = nw ? nw[k0 + 8 * i + r] : 1.f; d[0] = v[i].x * s; d[1] = v[i].y * s; d[2] = v[i].z * s; d[3] = v[i].w * s; } }
.LBB0_25:
	s_lshl_b32 s8, s11, 6
	v_or_b32_e32 v40, s8, v224
	s_ashr_i32 s11, s10, 31
	v_lshl_add_u64 v[2:3], s[10:11], 2, v[36:37]
	v_or_b32_e32 v6, 8, v40
	v_mad_i64_i32 v[4:5], s[10:11], v40, s21, v[2:3]
	v_mad_i64_i32 v[6:7], s[10:11], v6, s21, v[2:3]
	global_load_dwordx4 v[30:33], v[4:5], off
	global_load_dwordx4 v[26:29], v[6:7], off
	v_or_b32_e32 v4, 16, v40
	v_or_b32_e32 v6, 24, v40
	v_mad_i64_i32 v[4:5], s[10:11], v4, s21, v[2:3]
	v_mad_i64_i32 v[6:7], s[10:11], v6, s21, v[2:3]
	global_load_dwordx4 v[22:25], v[4:5], off
	global_load_dwordx4 v[18:21], v[6:7], off
	v_or_b32_e32 v4, 32, v40
	v_or_b32_e32 v6, 40, v40
	v_mad_i64_i32 v[4:5], s[10:11], v4, s21, v[2:3]
	v_mad_i64_i32 v[6:7], s[10:11], v6, s21, v[2:3]
	global_load_dwordx4 v[14:17], v[4:5], off
	global_load_dwordx4 v[10:13], v[6:7], off
	v_or_b32_e32 v4, 48, v40
	v_or_b32_e32 v6, 56, v40
	v_mad_i64_i32 v[4:5], s[10:11], v4, s21, v[2:3]
	v_mad_i64_i32 v[2:3], s[10:11], v6, s21, v[2:3]
	global_load_dwordx4 v[6:9], v[4:5], off
	s_nop 0
	global_load_dwordx4 v[2:5], v[2:3], off
	v_ashrrev_i32_e32 v41, 31, v40
	v_lshl_add_u64 v[40:41], v[40:41], 2, s[18:19]
	global_load_dword v245, v[40:41], off
	global_load_dword v246, v[40:41], off offset:32
	global_load_dword v247, v[40:41], off offset:64
	global_load_dword v248, v[40:41], off offset:96
	global_load_dword v249, v[40:41], off offset:128
	global_load_dword v251, v[40:41], off offset:160
	global_load_dword v252, v[40:41], off offset:192
	global_load_dword v253, v[40:41], off offset:224
	s_waitcnt vmcnt(0)
	v_mul_f32_e32 v30, v245, v30
	v_mul_f32_e32 v31, v245, v31
	v_mul_f32_e32 v32, v245, v32
	v_mul_f32_e32 v33, v245, v33
	v_mul_f32_e32 v26, v246, v26
	v_mul_f32_e32 v27, v246, v27
	v_mul_f32_e32 v28, v246, v28
	v_mul_f32_e32 v29, v246, v29
	v_mul_f32_e32 v22, v247, v22
	v_mul_f32_e32 v23, v247, v23
	v_mul_f32_e32 v24, v247, v24
	v_mul_f32_e32 v25, v247, v25
	v_mul_f32_e32 v18, v248, v18
	v_mul_f32_e32 v19, v248, v19
	v_mul_f32_e32 v20, v248, v20
	v_mul_f32_e32 v21, v248, v21
	v_mul_f32_e32 v14, v249, v14
	v_mul_f32_e32 v15, v249, v15
	v_mul_f32_e32 v16, v249, v16
	v_mul_f32_e32 v17, v249, v17
	v_mul_f32_e32 v10, v251, v10
	v_mul_f32_e32 v11, v251, v11
	v_mul_f32_e32 v12, v251, v12
	v_mul_f32_e32 v13, v251, v13
	v_mul_f32_e32 v6, v252, v6
	v_mul_f32_e32 v7, v252, v7
	v_mul_f32_e32 v8, v252, v8
	v_mul_f32_e32 v9, v252, v9
	v_mul_f32_e32 v2, v253, v2
	v_mul_f32_e32 v3, v253, v3
	v_mul_f32_e32 v4, v253, v4
	v_mul_f32_e32 v5, v253, v5
	ds_write2_b32 v46, v30, v31 offset1:1
	ds_write2_b32 v46, v32, v33 offset0:2 offset1:3
	v_add_u32_e32 v254, 0x420, v46
	ds_write2_b32 v254, v26, v27 offset1:1
	ds_write2_b32 v254, v28, v29 offset0:2 offset1:3
	v_add_u32_e32 v254, 0x840, v46
	ds_write2_b32 v254, v22, v23 offset1:1
	ds_write2_b32 v254, v24, v25 offset0:2 offset1:3
	v_add_u32_e32 v254, 0xc60, v46
	ds_write2_b32 v254, v18, v19 offset1:1
	ds_write2_b32 v254, v20, v21 offset0:2 offset1:3
	v_add_u32_e32 v254, 0x1080, v46
	ds_write2_b32 v254, v14, v15 offset1:1
	ds_write2_b32 v254, v16, v17 offset0:2 offset1:3
	v_add_u32_e32 v254, 0x14a0, v46
	ds_write2_b32 v254, v10, v11 offset1:1
	ds_write2_b32 v254, v12, v13 offset0:2 offset1:3
	v_add_u32_e32 v254, 0x18c0, v46
	ds_write2_b32 v254, v6, v7 offset1:1
	ds_write2_b32 v254, v8, v9 offset0:2 offset1:3
	v_add_u32_e32 v254, 0x1ce0, v46
	ds_write2_b32 v254, v2, v3 offset1:1
	ds_write2_b32 v254, v4, v5 offset0:2 offset1:3
	s_branch .LBB0_20

; #define LAS __attribute__((address_space(3)))
; __device__ __forceinline__ unsigned pkbf(float lo, float hi) { const f32x2_m v = {lo, hi}; const bf16x2_m b = __builtin_convertvector(v, bf16x2_m); return __builtin_bit_cast(unsigned, b); }
; __device__ __forceinline__ void tr_item(const float* W, const float* nw, int K, int N, bf16* WT, int k0, int n0, int drow0, LAS float* scr, int lane) {
;     { const int r = lane >> 3, c4 = lane & 7; f32x4 v[8];
; #pragma unroll
;       for (int i = 0; i < 8; ++i) v[i] = *(const f32x4*)(W + (size_t)(k0 + 8 * i + r) * N + n0 + 4 * c4);
; #pragma unroll
;       for (int i = 0; i < 8; ++i) { LAS float* d = scr + (8 * i + r) * 33 + 4 * c4; const float s = nw ? nw[k0 + 8 * i + r] : 1.f; d[0] = v[i].x * s; d[1] = v[i].y * s; d[2] = v[i].z * s; d[3] = v[i].w * s; } }
;     asm volatile("s_waitcnt lgkmcnt(0)" ::: "memory");
;     const int c = lane & 7;
; #pragma unroll
;     for (int j = 0; j < 4; ++j) { const int n = (lane >> 3) + 8 * j; const LAS float* s = scr + (8 * c) * 33 + n;
;         v4u o; o.x = pkbf(s[0 * 33], s[1 * 33]); o.y = pkbf(s[2 * 33], s[3 * 33]); o.z = pkbf(s[4 * 33], s[5 * 33]); o.w = pkbf(s[6 * 33], s[7 * 33]);
;         *(v4u*)(WT + (size_t)(drow0 + n) * K + k0 + 8 * c) = o; }
;     asm volatile("s_waitcnt lgkmcnt(0)" ::: "memory");
; }
; template <int MODE> __device__ __forceinline__ void conv_mat(const float* W, const float* nw, int K, int N, bf16* WT, LAS float* scr, int gw, int NGW, int lane) {
;     const int nblk = N / 32, nitems = (K / 64) * nblk;
;     for (int it = gw; it < nitems; it += NGW) { const int kb = it / nblk, nb = it % nblk, n0 = 32 * nb; int d = n0;
;         if (MODE == 1) { d = (n0 < DFF) ? 256 * (n0 / 128) + (n0 % 128) : 256 * ((n0 - DFF) / 128) + 128 + ((n0 - DFF) % 128); }
;         tr_item(W, nw, K, N, WT, 64 * kb, n0, d, scr, lane); }
.LBB0_38:
	s_waitcnt lgkmcnt(0)
	ds_read2_b32 v[6:7], v1 offset0:33 offset1:41
	ds_read2_b32 v[8:9], v1 offset1:8
	ds_read2_b32 v[10:11], v1 offset0:66 offset1:74
	ds_read2_b32 v[12:13], v1 offset0:99 offset1:107
	ds_read2_b32 v[14:15], v1 offset0:132 offset1:140
	ds_read2_b32 v[16:17], v1 offset0:165 offset1:173
	ds_read2_b32 v[18:19], v1 offset0:198 offset1:206
	ds_read2_b32 v[20:21], v1 offset0:231 offset1:239
	v_add_u32_e32 v24, s4, v224
	s_ashr_i32 s9, s8, 31
	v_ashrrev_i32_e32 v25, 31, v24
	v_lshl_add_u64 v[22:23], s[8:9], 1, v[38:39]
	v_lshlrev_b64 v[26:27], 12, v[24:25]
	s_waitcnt lgkmcnt(6)
	v_cvt_pk_bf16_f32 v2, v8, v6
	s_waitcnt lgkmcnt(4)
	v_cvt_pk_bf16_f32 v3, v10, v12
	s_waitcnt lgkmcnt(2)
	v_cvt_pk_bf16_f32 v4, v14, v16
	s_waitcnt lgkmcnt(0)
	v_cvt_pk_bf16_f32 v5, v18, v20
	v_lshl_add_u64 v[26:27], v[22:23], 0, v[26:27]
	v_add_u32_e32 v6, 8, v24
	global_store_dwordx4 v[26:27], v[2:5], off
	s_add_i32 s14, s14, s64
	s_add_i32 s3, s3, s10
	v_cvt_pk_bf16_f32 v2, v9, v7
	v_ashrrev_i32_e32 v7, 31, v6
	v_cvt_pk_bf16_f32 v3, v11, v13
	v_cvt_pk_bf16_f32 v4, v15, v17
	v_cvt_pk_bf16_f32 v5, v19, v21
	v_lshlrev_b64 v[6:7], 12, v[6:7]
	ds_read2_b32 v[8:9], v1 offset0:49 offset1:57
	ds_read2_b32 v[10:11], v1 offset0:16 offset1:24
	ds_read2_b32 v[12:13], v1 offset0:82 offset1:90
	ds_read2_b32 v[14:15], v1 offset0:115 offset1:123
	ds_read2_b32 v[16:17], v1 offset0:148 offset1:156
	ds_read2_b32 v[18:19], v1 offset0:181 offset1:189
	ds_read2_b32 v[20:21], v1 offset0:214 offset1:222
	ds_read2_b32 v[26:27], v1 offset0:247 offset1:255
	v_lshl_add_u64 v[6:7], v[22:23], 0, v[6:7]
	global_store_dwordx4 v[6:7], v[2:5], off
	v_add_u32_e32 v6, 16, v24
	v_ashrrev_i32_e32 v7, 31, v6
	v_lshlrev_b64 v[6:7], 12, v[6:7]
	s_waitcnt lgkmcnt(6)
	v_cvt_pk_bf16_f32 v2, v10, v8
	s_waitcnt lgkmcnt(4)
	v_cvt_pk_bf16_f32 v3, v12, v14
	s_waitcnt lgkmcnt(2)
	v_cvt_pk_bf16_f32 v4, v16, v18
	s_waitcnt lgkmcnt(0)
	v_cvt_pk_bf16_f32 v5, v20, v26
	v_lshl_add_u64 v[6:7], v[22:23], 0, v[6:7]
	global_store_dwordx4 v[6:7], v[2:5], off
	v_add_u32_e32 v6, 24, v24
	v_ashrrev_i32_e32 v7, 31, v6
	v_lshlrev_b64 v[6:7], 12, v[6:7]
	v_cvt_pk_bf16_f32 v2, v11, v9
	v_cvt_pk_bf16_f32 v3, v13, v15
	v_cvt_pk_bf16_f32 v4, v17, v19
	v_cvt_pk_bf16_f32 v5, v21, v27
	v_lshl_add_u64 v[6:7], v[22:23], 0, v[6:7]
	global_store_dwordx4 v[6:7], v[2:5], off
	s_waitcnt lgkmcnt(0)
	s_cmpk_lt_i32 s14, 0x2c00
	s_cbranch_scc0 .LBB0_47
.LBB0_39:
	s_mul_hi_i32 s4, s14, 0x2e8ba2e9
	s_lshr_b32 s5, s4, 31
	s_ashr_i32 s4, s4, 6
	s_add_i32 s5, s4, s5
	s_mul_i32 s4, s5, 0xffffd400
	s_add_i32 s4, s3, s4
	s_lshl_b32 s8, s5, 6
	v_or_b32_e32 v40, s8, v224
	s_ashr_i32 s5, s4, 31
	v_lshl_add_u64 v[2:3], s[4:5], 2, v[36:37]
	v_or_b32_e32 v6, 8, v40
	v_mad_i64_i32 v[4:5], s[20:21], v40, s11, v[2:3]
	v_mad_i64_i32 v[6:7], s[20:21], v6, s11, v[2:3]
	global_load_dwordx4 v[30:33], v[4:5], off
	global_load_dwordx4 v[26:29], v[6:7], off
	v_or_b32_e32 v4, 16, v40
	v_or_b32_e32 v6, 24, v40
	v_mad_i64_i32 v[4:5], s[20:21], v4, s11, v[2:3]
	v_mad_i64_i32 v[6:7], s[20:21], v6, s11, v[2:3]
	global_load_dwordx4 v[22:25], v[4:5], off
	global_load_dwordx4 v[18:21], v[6:7], off
	v_or_b32_e32 v4, 32, v40
	v_or_b32_e32 v6, 40, v40
	v_mad_i64_i32 v[4:5], s[20:21], v4, s11, v[2:3]
	v_mad_i64_i32 v[6:7], s[20:21], v6, s11, v[2:3]
	global_load_dwordx4 v[14:17], v[4:5], off
	global_load_dwordx4 v[10:13], v[6:7], off
	v_or_b32_e32 v4, 48, v40
	v_or_b32_e32 v6, 56, v40
	v_mad_i64_i32 v[4:5], s[20:21], v4, s11, v[2:3]
	v_mad_i64_i32 v[2:3], s[20:21], v6, s11, v[2:3]
	global_load_dwordx4 v[6:9], v[4:5], off
	s_nop 0
	global_load_dwordx4 v[2:5], v[2:3], off
	v_ashrrev_i32_e32 v41, 31, v40
	v_lshl_add_u64 v[40:41], v[40:41], 2, s[24:25]
	global_load_dword v245, v[40:41], off
	global_load_dword v246, v[40:41], off offset:32
	global_load_dword v247, v[40:41], off offset:64
	global_load_dword v248, v[40:41], off offset:96
	global_load_dword v249, v[40:41], off offset:128
	global_load_dword v251, v[40:41], off offset:160
	global_load_dword v252, v[40:41], off offset:192
	global_load_dword v253, v[40:41], off offset:224
	s_waitcnt vmcnt(0)
	v_mul_f32_e32 v30, v245, v30
	v_mul_f32_e32 v31, v245, v31
	v_mul_f32_e32 v32, v245, v32
	v_mul_f32_e32 v33, v245, v33
	v_mul_f32_e32 v26, v246, v26
	v_mul_f32_e32 v27, v246, v27
	v_mul_f32_e32 v28, v246, v28
	v_mul_f32_e32 v29, v246, v29
	v_mul_f32_e32 v22, v247, v22
	v_mul_f32_e32 v23, v247, v23
	v_mul_f32_e32 v24, v247, v24
	v_mul_f32_e32 v25, v247, v25
	v_mul_f32_e32 v18, v248, v18
	v_mul_f32_e32 v19, v248, v19
	v_mul_f32_e32 v20, v248, v20
	v_mul_f32_e32 v21, v248, v21
	v_mul_f32_e32 v14, v249, v14
	v_mul_f32_e32 v15, v249, v15
	v_mul_f32_e32 v16, v249, v16
	v_mul_f32_e32 v17, v249, v17
	v_mul_f32_e32 v10, v251, v10
	v_mul_f32_e32 v11, v251, v11
	v_mul_f32_e32 v12, v251, v12
	v_mul_f32_e32 v13, v251, v13
	v_mul_f32_e32 v6, v252, v6
	v_mul_f32_e32 v7, v252, v7
	v_mul_f32_e32 v8, v252, v8
	v_mul_f32_e32 v9, v252, v9
	v_mul_f32_e32 v2, v253, v2
	v_mul_f32_e32 v3, v253, v3
	v_mul_f32_e32 v4, v253, v4
	v_mul_f32_e32 v5, v253, v5
	ds_write2_b32 v35, v30, v31 offset1:1
	ds_write2_b32 v35, v32, v33 offset0:2 offset1:3
	v_add_u32_e32 v254, 0x420, v35
	ds_write2_b32 v254, v26, v27 offset1:1
	ds_write2_b32 v254, v28, v29 offset0:2 offset1:3
	v_add_u32_e32 v254, 0x840, v35
	ds_write2_b32 v254, v22, v23 offset1:1
	ds_write2_b32 v254, v24, v25 offset0:2 offset1:3
	v_add_u32_e32 v254, 0xc60, v35
	ds_write2_b32 v254, v18, v19 offset1:1
	ds_write2_b32 v254, v20, v21 offset0:2 offset1:3
	v_add_u32_e32 v254, 0x1080, v35
	ds_write2_b32 v254, v14, v15 offset1:1
	ds_write2_b32 v254, v16, v17 offset0:2 offset1:3
	v_add_u32_e32 v254, 0x14a0, v35
	ds_write2_b32 v254, v10, v11 offset1:1
	ds_write2_b32 v254, v12, v13 offset0:2 offset1:3
	v_add_u32_e32 v254, 0x18c0, v35
	ds_write2_b32 v254, v6, v7 offset1:1
	ds_write2_b32 v254, v8, v9 offset0:2 offset1:3
	v_add_u32_e32 v254, 0x1ce0, v35
	ds_write2_b32 v254, v2, v3 offset1:1
	ds_write2_b32 v254, v4, v5 offset0:2 offset1:3
	s_branch .LBB0_38

; #define LAS __attribute__((address_space(3)))
; __device__ __forceinline__ unsigned pkbf(float lo, float hi) { const f32x2_m v = {lo, hi}; const bf16x2_m b = __builtin_convertvector(v, bf16x2_m); return __builtin_bit_cast(unsigned, b); }
; __device__ __forceinline__ void tr_item(const float* W, const float* nw, int K, int N, bf16* WT, int k0, int n0, int drow0, LAS float* scr, int lane) {
;     ...
;     asm volatile("s_waitcnt lgkmcnt(0)" ::: "memory");
;     const int c = lane & 7;
; #pragma unroll
;     for (int j = 0; j < 4; ++j) { const int n = (lane >> 3) + 8 * j; const LAS float* s = scr + (8 * c) * 33 + n;
;         v4u o; o.x = pkbf(s[0 * 33], s[1 * 33]); o.y = pkbf(s[2 * 33], s[3 * 33]); o.z = pkbf(s[4 * 33], s[5 * 33]); o.w = pkbf(s[6 * 33], s[7 * 33]);
;         *(v4u*)(WT + (size_t)(drow0 + n) * K + k0 + 8 * c) = o; }
;     asm volatile("s_waitcnt lgkmcnt(0)" ::: "memory");
.LBB0_1763:
	s_waitcnt lgkmcnt(0)
	ds_read2_b32 v[4:5], v43 offset0:33 offset1:41
	ds_read2_b32 v[6:7], v43 offset1:8
	ds_read2_b32 v[8:9], v43 offset0:66 offset1:74
	ds_read2_b32 v[10:11], v43 offset0:99 offset1:107
	ds_read2_b32 v[12:13], v43 offset0:132 offset1:140
	ds_read2_b32 v[14:15], v43 offset0:165 offset1:173
	ds_read2_b32 v[16:17], v43 offset0:198 offset1:206
	ds_read2_b32 v[18:19], v43 offset0:231 offset1:239
	v_add_u32_e32 v22, s17, v224
	s_ashr_i32 s1, s0, 31
	v_ashrrev_i32_e32 v23, 31, v22
	v_lshl_add_u64 v[20:21], s[0:1], 1, v[34:35]
	v_lshlrev_b64 v[22:23], 12, v[22:23]
	s_waitcnt lgkmcnt(6)
	v_cvt_pk_bf16_f32 v0, v6, v4
	s_waitcnt lgkmcnt(4)
	v_cvt_pk_bf16_f32 v1, v8, v10
	s_waitcnt lgkmcnt(2)
	v_cvt_pk_bf16_f32 v2, v12, v14
	s_waitcnt lgkmcnt(0)
	v_cvt_pk_bf16_f32 v3, v16, v18
	v_lshl_add_u64 v[22:23], v[20:21], 0, v[22:23]
	v_add_u32_e32 v4, s17, v39
	global_store_dwordx4 v[22:23], v[0:3], off
	s_add_i32 s16, s16, s64
	s_add_i32 s3, s3, s12
	v_cvt_pk_bf16_f32 v0, v7, v5
	v_ashrrev_i32_e32 v5, 31, v4
	v_cvt_pk_bf16_f32 v1, v9, v11
	v_cvt_pk_bf16_f32 v2, v13, v15
	v_cvt_pk_bf16_f32 v3, v17, v19
	v_lshlrev_b64 v[4:5], 12, v[4:5]
	ds_read2_b32 v[6:7], v43 offset0:49 offset1:57
	ds_read2_b32 v[8:9], v43 offset0:16 offset1:24
	ds_read2_b32 v[10:11], v43 offset0:82 offset1:90
	ds_read2_b32 v[12:13], v43 offset0:115 offset1:123
	ds_read2_b32 v[14:15], v43 offset0:148 offset1:156
	ds_read2_b32 v[16:17], v43 offset0:181 offset1:189
	ds_read2_b32 v[18:19], v43 offset0:214 offset1:222
	ds_read2_b32 v[22:23], v43 offset0:247 offset1:255
	v_lshl_add_u64 v[4:5], v[20:21], 0, v[4:5]
	global_store_dwordx4 v[4:5], v[0:3], off
	v_add_u32_e32 v4, s17, v41
	v_ashrrev_i32_e32 v5, 31, v4
	v_lshlrev_b64 v[4:5], 12, v[4:5]
	s_waitcnt lgkmcnt(6)
	v_cvt_pk_bf16_f32 v0, v8, v6
	s_waitcnt lgkmcnt(4)
	v_cvt_pk_bf16_f32 v1, v10, v12
	s_waitcnt lgkmcnt(2)
	v_cvt_pk_bf16_f32 v2, v14, v16
	s_waitcnt lgkmcnt(0)
	v_cvt_pk_bf16_f32 v3, v18, v22
	v_lshl_add_u64 v[4:5], v[20:21], 0, v[4:5]
	global_store_dwordx4 v[4:5], v[0:3], off
	v_add_u32_e32 v4, s17, v42
	v_ashrrev_i32_e32 v5, 31, v4
	v_lshlrev_b64 v[4:5], 12, v[4:5]
	v_cvt_pk_bf16_f32 v0, v9, v7
	v_cvt_pk_bf16_f32 v1, v11, v13
	v_cvt_pk_bf16_f32 v2, v15, v17
	v_cvt_pk_bf16_f32 v3, v19, v23
	v_lshl_add_u64 v[4:5], v[20:21], 0, v[4:5]
	global_store_dwordx4 v[4:5], v[0:3], off
	s_waitcnt lgkmcnt(0)
	s_add_i32 s13, s13, s14
	s_cmpk_lt_i32 s16, 0x2c00
	s_cbranch_scc0 .LBB0_1776

; #define LAS __attribute__((address_space(3)))
; __device__ __forceinline__ void tr_item(const float* W, const float* nw, int K, int N, bf16* WT, int k0, int n0, int drow0, LAS float* scr, int lane) {
;     { const int r = lane >> 3, c4 = lane & 7; f32x4 v[8];
; #pragma unroll
;       for (int i = 0; i < 8; ++i) v[i] = *(const f32x4*)(W + (size_t)(k0 + 8 * i + r) * N + n0 + 4 * c4);
; #pragma unroll
;       for (int i = 0; i < 8; ++i) { LAS float* d = scr + (8 * i + r) * 33 + 4 * c4; const float s = nw ? nw[k0 + 8 * i + r] : 1.f; d[0] = v[i].x * s; d[1] = v[i].y * s; d[2] = v[i].z * s; d[3] = v[i].w * s; } }
.LBB0_1768:
	s_lshl_b32 s0, s11, 6
	v_or_b32_e32 v36, s0, v224
	s_ashr_i32 s11, s10, 31
	v_lshl_add_u64 v[0:1], s[10:11], 2, v[32:33]
	v_or_b32_e32 v4, 8, v36
	v_mad_i64_i32 v[2:3], s[10:11], v36, s15, v[0:1]
	v_mad_i64_i32 v[4:5], s[10:11], v4, s15, v[0:1]
	global_load_dwordx4 v[28:31], v[2:3], off
	global_load_dwordx4 v[24:27], v[4:5], off
	v_or_b32_e32 v2, 16, v36
	v_or_b32_e32 v4, 24, v36
	v_mad_i64_i32 v[2:3], s[10:11], v2, s15, v[0:1]
	v_mad_i64_i32 v[4:5], s[10:11], v4, s15, v[0:1]
	global_load_dwordx4 v[20:23], v[2:3], off
	global_load_dwordx4 v[16:19], v[4:5], off
	v_or_b32_e32 v2, 32, v36
	v_or_b32_e32 v4, 40, v36
	v_mad_i64_i32 v[2:3], s[10:11], v2, s15, v[0:1]
	v_mad_i64_i32 v[4:5], s[10:11], v4, s15, v[0:1]
	global_load_dwordx4 v[12:15], v[2:3], off
	global_load_dwordx4 v[8:11], v[4:5], off
	v_or_b32_e32 v2, 48, v36
	v_or_b32_e32 v4, 56, v36
	v_mad_i64_i32 v[2:3], s[10:11], v2, s15, v[0:1]
	v_mad_i64_i32 v[0:1], s[10:11], v4, s15, v[0:1]
	global_load_dwordx4 v[4:7], v[2:3], off
	s_nop 0
	global_load_dwordx4 v[0:3], v[0:1], off
	v_ashrrev_i32_e32 v37, 31, v36
	v_lshl_add_u64 v[36:37], v[36:37], 2, s[84:85]
	global_load_dword v245, v[36:37], off
	global_load_dword v246, v[36:37], off offset:32
	global_load_dword v247, v[36:37], off offset:64
	global_load_dword v248, v[36:37], off offset:96
	global_load_dword v249, v[36:37], off offset:128
	global_load_dword v251, v[36:37], off offset:160
	global_load_dword v252, v[36:37], off offset:192
	global_load_dword v253, v[36:37], off offset:224
	s_waitcnt vmcnt(0)
	v_mul_f32_e32 v28, v245, v28
	v_mul_f32_e32 v29, v245, v29
	v_mul_f32_e32 v30, v245, v30
	v_mul_f32_e32 v31, v245, v31
	v_mul_f32_e32 v24, v246, v24
	v_mul_f32_e32 v25, v246, v25
	v_mul_f32_e32 v26, v246, v26
	v_mul_f32_e32 v27, v246, v27
	v_mul_f32_e32 v20, v247, v20
	v_mul_f32_e32 v21, v247, v21
	v_mul_f32_e32 v22, v247, v22
	v_mul_f32_e32 v23, v247, v23
	v_mul_f32_e32 v16, v248, v16
	v_mul_f32_e32 v17, v248, v17
	v_mul_f32_e32 v18, v248, v18
	v_mul_f32_e32 v19, v248, v19
	v_mul_f32_e32 v12, v249, v12
	v_mul_f32_e32 v13, v249, v13
	v_mul_f32_e32 v14, v249, v14
	v_mul_f32_e32 v15, v249, v15
	v_mul_f32_e32 v8, v251, v8
	v_mul_f32_e32 v9, v251, v9
	v_mul_f32_e32 v10, v251, v10
	v_mul_f32_e32 v11, v251, v11
	v_mul_f32_e32 v4, v252, v4
	v_mul_f32_e32 v5, v252, v5
	v_mul_f32_e32 v6, v252, v6
	v_mul_f32_e32 v7, v252, v7
	v_mul_f32_e32 v0, v253, v0
	v_mul_f32_e32 v1, v253, v1
	v_mul_f32_e32 v2, v253, v2
	v_mul_f32_e32 v3, v253, v3
	ds_write2_b32 v44, v28, v29 offset1:1
	ds_write2_b32 v44, v30, v31 offset0:2 offset1:3
	v_add_u32_e32 v254, 0x420, v44
	ds_write2_b32 v254, v24, v25 offset1:1
	ds_write2_b32 v254, v26, v27 offset0:2 offset1:3
	v_add_u32_e32 v254, 0x840, v44
	ds_write2_b32 v254, v20, v21 offset1:1
	ds_write2_b32 v254, v22, v23 offset0:2 offset1:3
	v_add_u32_e32 v254, 0xc60, v44
	ds_write2_b32 v254, v16, v17 offset1:1
	ds_write2_b32 v254, v18, v19 offset0:2 offset1:3
	v_add_u32_e32 v254, 0x1080, v44
	ds_write2_b32 v254, v12, v13 offset1:1
	ds_write2_b32 v254, v14, v15 offset0:2 offset1:3
	v_add_u32_e32 v254, 0x14a0, v44
	ds_write2_b32 v254, v8, v9 offset1:1
	ds_write2_b32 v254, v10, v11 offset0:2 offset1:3
	v_add_u32_e32 v254, 0x18c0, v44
	ds_write2_b32 v254, v4, v5 offset1:1
	ds_write2_b32 v254, v6, v7 offset0:2 offset1:3
	v_add_u32_e32 v254, 0x1ce0, v44
	ds_write2_b32 v254, v0, v1 offset1:1
	ds_write2_b32 v254, v2, v3 offset0:2 offset1:3
	s_branch .LBB0_1763

; __global__ void __launch_bounds__(512, 2) fwd_megakernel(Args a) {
	.amdhsa_kernel _Z14fwd_megakernel4Args
		.amdhsa_group_segment_fixed_size 0
		.amdhsa_private_segment_fixed_size 0
		.amdhsa_kernarg_size 432
		.amdhsa_user_sgpr_count 2
		.amdhsa_user_sgpr_dispatch_ptr 0
		.amdhsa_user_sgpr_queue_ptr 0
		.amdhsa_user_sgpr_kernarg_segment_ptr 1
		.amdhsa_user_sgpr_dispatch_id 0
		.amdhsa_user_sgpr_kernarg_preload_length 0
		.amdhsa_user_sgpr_kernarg_preload_offset 0
		.amdhsa_user_sgpr_private_segment_size 0
		.amdhsa_uses_dynamic_stack 0
		.amdhsa_enable_private_segment 0
		.amdhsa_system_sgpr_workgroup_id_x 1
		.amdhsa_system_sgpr_workgroup_id_y 0
		.amdhsa_system_sgpr_workgroup_id_z 0
		.amdhsa_system_sgpr_workgroup_info 0
		.amdhsa_system_vgpr_workitem_id 2
		.amdhsa_next_free_vgpr 256
		.amdhsa_next_free_sgpr 98
		.amdhsa_accum_offset 256
		.amdhsa_reserve_vcc 1
		.amdhsa_float_round_mode_32 0
		.amdhsa_float_round_mode_16_64 0
		.amdhsa_float_denorm_mode_32 3
		.amdhsa_float_denorm_mode_16_64 3
		.amdhsa_dx10_clamp 1
		.amdhsa_ieee_mode 1
		.amdhsa_fp16_overflow 0
		.amdhsa_tg_split 0
		.amdhsa_exception_fp_ieee_invalid_op 0
		.amdhsa_exception_fp_denorm_src 0
		.amdhsa_exception_fp_ieee_div_zero 0
		.amdhsa_exception_fp_ieee_overflow 0
		.amdhsa_exception_fp_ieee_underflow 0
		.amdhsa_exception_fp_ieee_inexact 0
		.amdhsa_exception_int_div_zero 0
	.end_amdhsa_kernel

; __global__ void __launch_bounds__(512, 2) fwd_megakernel(Args a) {
amdhsa.kernels:
  - .agpr_count:     0
    .args:
      - .offset:         0
        .size:           176
        .value_kind:     by_value
      - .offset:         176
        .size:           4
        .value_kind:     hidden_block_count_x
      - .offset:         180
        .size:           4
        .value_kind:     hidden_block_count_y
      - .offset:         184
        .size:           4
        .value_kind:     hidden_block_count_z
      - .offset:         188
        .size:           2
        .value_kind:     hidden_group_size_x
      - .offset:         190
        .size:           2
        .value_kind:     hidden_group_size_y
      - .offset:         192
        .size:           2
        .value_kind:     hidden_group_size_z
      - .offset:         194
        .size:           2
        .value_kind:     hidden_remainder_x
      - .offset:         196
        .size:           2
        .value_kind:     hidden_remainder_y
      - .offset:         198
        .size:           2
        .value_kind:     hidden_remainder_z
      - .offset:         216
        .size:           8
        .value_kind:     hidden_global_offset_x
      - .offset:         224
        .size:           8
        .value_kind:     hidden_global_offset_y
      - .offset:         232
        .size:           8
        .value_kind:     hidden_global_offset_z
      - .offset:         240
        .size:           2
        .value_kind:     hidden_grid_dims
      - .offset:         264
        .size:           8
        .value_kind:     hidden_multigrid_sync_arg
      - .offset:         296
        .size:           4
        .value_kind:     hidden_dynamic_lds_size
    .group_segment_fixed_size: 0
    .kernarg_segment_align: 8
    .kernarg_segment_size: 432
    .language:       OpenCL C
    .language_version:
      - 2
      - 0
    .max_flat_workgroup_size: 512
    .name:           _Z14fwd_megakernel4Args
    .private_segment_fixed_size: 0
    .sgpr_count:     104
    .sgpr_spill_count: 57
    .symbol:         _Z14fwd_megakernel4Args.kd
    .uniform_work_group_size: 1
    .uses_dynamic_stack: false
    .vgpr_count:     256
    .vgpr_spill_count: 0
    .wavefront_size: 64
